# v23 + XNACK-only s_nop pads removed between back-to-back row loads in the pooling loop
# baseline (speedup 1.0000x reference)
.LBB0_158:
	v_add_co_u32_e32 v4, vcc, s36, v142
	v_lshl_add_u32 v132, s23, 9, v182
	s_nop 0
	v_addc_co_u32_e32 v5, vcc, -1, v143, vcc
	v_add_co_u32_e32 v8, vcc, s37, v142
	global_load_dwordx4 v[64:67], v[4:5], off offset:-4096
	global_load_dwordx4 v[4:7], v[4:5], off
	v_addc_co_u32_e32 v9, vcc, -1, v143, vcc
	v_add_co_u32_e32 v16, vcc, s38, v142
	global_load_dwordx4 v[12:15], v[8:9], off offset:-4096
	global_load_dwordx4 v[8:11], v[8:9], off
	v_addc_co_u32_e32 v17, vcc, -1, v143, vcc
	global_load_dwordx4 v[20:23], v[16:17], off offset:-4096
	global_load_dwordx4 v[16:19], v[16:17], off
	v_add_co_u32_e32 v24, vcc, s39, v142
	s_nop 1
	v_addc_co_u32_e32 v25, vcc, -1, v143, vcc
	v_add_co_u32_e32 v32, vcc, s40, v142
	s_nop 1
	v_addc_co_u32_e32 v33, vcc, -1, v143, vcc
	v_add_co_u32_e32 v40, vcc, s41, v142
	s_nop 1
	v_addc_co_u32_e32 v41, vcc, -1, v143, vcc
	v_add_co_u32_e32 v52, vcc, s42, v142
	s_nop 1
	v_addc_co_u32_e32 v53, vcc, -1, v143, vcc
	global_load_dwordx4 v[60:63], v[142:143], off offset:-4096
	global_load_dwordx4 v[56:59], v[142:143], off
	global_load_dwordx4 v[28:31], v[24:25], off offset:-4096
	global_load_dwordx4 v[24:27], v[24:25], off
	global_load_dwordx4 v[36:39], v[32:33], off offset:-4096
	global_load_dwordx4 v[32:35], v[32:33], off
	global_load_dwordx4 v[44:47], v[40:41], off offset:-4096
	global_load_dwordx4 v[40:43], v[40:41], off
	global_load_dwordx4 v[48:51], v[52:53], off offset:-4096
	global_load_dwordx4 v[52:55], v[52:53], off
	s_waitcnt vmcnt(15)
	v_mov_b32_e32 v148, v65
	s_waitcnt vmcnt(14)
	v_mov_b32_e32 v149, v5
	v_mov_b32_e32 v152, v67
	v_mov_b32_e32 v153, v7
	s_waitcnt vmcnt(13)
	v_mov_b32_e32 v156, v13
	s_waitcnt vmcnt(12)
	v_mov_b32_e32 v157, v9
	v_mov_b32_e32 v160, v15
	v_mov_b32_e32 v161, v11
	v_mov_b32_e32 v146, v64
	v_mov_b32_e32 v147, v4
	v_mov_b32_e32 v150, v66
	v_mov_b32_e32 v151, v6
	v_mov_b32_e32 v154, v12
	v_mov_b32_e32 v155, v8
	v_mov_b32_e32 v158, v14
	v_mov_b32_e32 v159, v10
	s_waitcnt vmcnt(11)
	v_mov_b32_e32 v164, v21
	s_waitcnt vmcnt(10)
	v_mov_b32_e32 v165, v17
	v_mov_b32_e32 v168, v23
	v_mov_b32_e32 v169, v19
	v_pk_mul_f32 v[148:149], v[148:149], v[148:149]
	v_pk_mul_f32 v[152:153], v[152:153], v[152:153]
	v_pk_mul_f32 v[156:157], v[156:157], v[156:157]
	v_pk_mul_f32 v[160:161], v[160:161], v[160:161]
	v_mov_b32_e32 v162, v20
	v_mov_b32_e32 v163, v16
	v_mov_b32_e32 v166, v22
	v_mov_b32_e32 v167, v18
	v_pk_mul_f32 v[164:165], v[164:165], v[164:165]
	v_pk_mul_f32 v[168:169], v[168:169], v[168:169]
	v_pk_fma_f32 v[146:147], v[146:147], v[146:147], v[148:149]
	v_pk_fma_f32 v[148:149], v[150:151], v[150:151], v[152:153]
	v_pk_fma_f32 v[150:151], v[154:155], v[154:155], v[156:157]
	v_pk_fma_f32 v[152:153], v[158:159], v[158:159], v[160:161]
	v_pk_fma_f32 v[154:155], v[162:163], v[162:163], v[164:165]
	v_pk_fma_f32 v[156:157], v[166:167], v[166:167], v[168:169]
	v_pk_add_f32 v[150:151], v[150:151], v[152:153]
	v_pk_add_f32 v[152:153], v[154:155], v[156:157]
	ds_bpermute_b32 v154, v129, v150
	ds_bpermute_b32 v155, v129, v151
	ds_bpermute_b32 v156, v129, v152
	ds_bpermute_b32 v157, v129, v153
	v_pk_add_f32 v[146:147], v[146:147], v[148:149]
	ds_bpermute_b32 v148, v129, v146
	s_waitcnt lgkmcnt(3)
	v_pk_add_f32 v[150:151], v[150:151], v[154:155]
	ds_bpermute_b32 v154, v184, v150
	ds_bpermute_b32 v155, v184, v151
	s_waitcnt lgkmcnt(3)
	v_pk_add_f32 v[152:153], v[152:153], v[156:157]
	ds_bpermute_b32 v156, v184, v152
	ds_bpermute_b32 v157, v184, v153
	ds_bpermute_b32 v149, v129, v147
	s_waitcnt lgkmcnt(3)
	v_pk_add_f32 v[150:151], v[150:151], v[154:155]
	ds_bpermute_b32 v154, v185, v150
	ds_bpermute_b32 v155, v185, v151
	s_waitcnt lgkmcnt(3)
	v_pk_add_f32 v[152:153], v[152:153], v[156:157]
	s_waitcnt lgkmcnt(2)
	v_pk_add_f32 v[146:147], v[146:147], v[148:149]
	ds_bpermute_b32 v148, v184, v146
	ds_bpermute_b32 v149, v184, v147
	s_waitcnt lgkmcnt(2)
	v_pk_add_f32 v[150:151], v[150:151], v[154:155]
	ds_bpermute_b32 v154, v186, v150
	ds_bpermute_b32 v155, v186, v151
	s_waitcnt lgkmcnt(2)
	v_pk_add_f32 v[146:147], v[146:147], v[148:149]
	ds_bpermute_b32 v148, v185, v146
	ds_bpermute_b32 v149, v185, v147
	s_waitcnt lgkmcnt(2)
	v_pk_add_f32 v[150:151], v[150:151], v[154:155]
	ds_bpermute_b32 v154, v185, v152
	ds_bpermute_b32 v155, v185, v153
	s_waitcnt lgkmcnt(2)
	v_pk_add_f32 v[146:147], v[146:147], v[148:149]
	ds_bpermute_b32 v148, v186, v146
	ds_bpermute_b32 v149, v186, v147
	s_waitcnt lgkmcnt(2)
	v_pk_add_f32 v[152:153], v[152:153], v[154:155]
	ds_bpermute_b32 v154, v186, v152
	ds_bpermute_b32 v155, v186, v153
	s_waitcnt vmcnt(9)
	v_mov_b32_e32 v174, v61
	s_waitcnt vmcnt(7)
	v_mov_b32_e32 v158, v29
	s_waitcnt vmcnt(6)
	v_mov_b32_e32 v159, v25
	v_mov_b32_e32 v156, v28
	v_mov_b32_e32 v157, v24
	s_waitcnt vmcnt(3)
	v_mov_b32_e32 v168, v45
	s_waitcnt vmcnt(2)
	v_mov_b32_e32 v169, v41
	v_mov_b32_e32 v166, v44
	v_mov_b32_e32 v167, v40
	v_pk_mul_f32 v[168:169], v[168:169], v[168:169]
	v_mov_b32_e32 v170, v47
	v_mov_b32_e32 v171, v43
	v_pk_fma_f32 v[166:167], v[166:167], v[166:167], v[168:169]
	v_mov_b32_e32 v168, v46
	v_mov_b32_e32 v169, v42
	v_pk_mul_f32 v[170:171], v[170:171], v[170:171]
	v_pk_mul_f32 v[158:159], v[158:159], v[158:159]
	v_pk_fma_f32 v[168:169], v[168:169], v[168:169], v[170:171]
	v_mov_b32_e32 v160, v31
	v_pk_add_f32 v[166:167], v[166:167], v[168:169]
	ds_bpermute_b32 v168, v129, v166
	ds_bpermute_b32 v169, v129, v167
	v_mov_b32_e32 v161, v27
	v_pk_fma_f32 v[156:157], v[156:157], v[156:157], v[158:159]
	v_mov_b32_e32 v158, v30
	v_mov_b32_e32 v159, v26
	v_pk_mul_f32 v[160:161], v[160:161], v[160:161]
	s_waitcnt lgkmcnt(0)
	v_pk_add_f32 v[166:167], v[166:167], v[168:169]
	v_pk_fma_f32 v[158:159], v[158:159], v[158:159], v[160:161]
	ds_bpermute_b32 v168, v184, v166
	ds_bpermute_b32 v169, v184, v167
	v_pk_add_f32 v[156:157], v[156:157], v[158:159]
	ds_bpermute_b32 v158, v129, v156
	ds_bpermute_b32 v159, v129, v157
	v_pk_add_f32 v[162:163], v[152:153], v[154:155]
	s_waitcnt lgkmcnt(2)
	v_pk_add_f32 v[166:167], v[166:167], v[168:169]
	ds_bpermute_b32 v168, v185, v166
	ds_bpermute_b32 v169, v185, v167
	s_waitcnt lgkmcnt(2)
	v_pk_add_f32 v[156:157], v[156:157], v[158:159]
	ds_bpermute_b32 v158, v184, v156
	ds_bpermute_b32 v159, v184, v157
	ds_bpermute_b32 v160, v187, v150
	s_waitcnt lgkmcnt(3)
	v_pk_add_f32 v[166:167], v[166:167], v[168:169]
	ds_bpermute_b32 v168, v186, v166
	ds_bpermute_b32 v169, v186, v167
	ds_bpermute_b32 v161, v187, v151
	ds_bpermute_b32 v164, v187, v162
	ds_bpermute_b32 v165, v187, v163
	s_waitcnt lgkmcnt(6)
	v_pk_add_f32 v[156:157], v[156:157], v[158:159]
	ds_bpermute_b32 v158, v185, v156
	ds_bpermute_b32 v159, v185, v157
	s_waitcnt vmcnt(1)
	v_mov_b32_e32 v170, v49
	s_waitcnt vmcnt(0)
	v_mov_b32_e32 v171, v53
	s_waitcnt lgkmcnt(5)
	v_pk_add_f32 v[166:167], v[166:167], v[168:169]
	v_mov_b32_e32 v168, v48
	v_mov_b32_e32 v169, v52
	v_pk_mul_f32 v[170:171], v[170:171], v[170:171]
	v_mov_b32_e32 v172, v51
	v_mov_b32_e32 v173, v55
	s_waitcnt lgkmcnt(4)
	v_pk_add_f32 v[152:153], v[150:151], v[160:161]
	s_waitcnt lgkmcnt(2)
	v_pk_add_f32 v[150:151], v[162:163], v[164:165]
	v_mov_b32_e32 v162, v37
	v_mov_b32_e32 v163, v33
	v_pk_fma_f32 v[168:169], v[168:169], v[168:169], v[170:171]
	v_mov_b32_e32 v170, v50
	v_mov_b32_e32 v171, v54
	v_pk_mul_f32 v[172:173], v[172:173], v[172:173]
	v_mov_b32_e32 v175, v57
	s_waitcnt lgkmcnt(0)
	v_pk_add_f32 v[158:159], v[156:157], v[158:159]
	v_mov_b32_e32 v156, v36
	v_mov_b32_e32 v157, v32
	v_pk_mul_f32 v[162:163], v[162:163], v[162:163]
	v_mov_b32_e32 v164, v39
	v_mov_b32_e32 v165, v35
	v_pk_fma_f32 v[170:171], v[170:171], v[170:171], v[172:173]
	v_mov_b32_e32 v172, v60
	v_mov_b32_e32 v173, v56
	v_pk_mul_f32 v[174:175], v[174:175], v[174:175]
	v_mov_b32_e32 v176, v63
	v_mov_b32_e32 v177, v59
	v_pk_fma_f32 v[156:157], v[156:157], v[156:157], v[162:163]
	v_mov_b32_e32 v162, v38
	v_mov_b32_e32 v163, v34
	v_pk_mul_f32 v[164:165], v[164:165], v[164:165]
	v_pk_fma_f32 v[172:173], v[172:173], v[172:173], v[174:175]
	v_mov_b32_e32 v174, v62
	v_mov_b32_e32 v175, v58
	v_pk_mul_f32 v[176:177], v[176:177], v[176:177]
	v_pk_fma_f32 v[162:163], v[162:163], v[162:163], v[164:165]
	v_pk_fma_f32 v[174:175], v[174:175], v[174:175], v[176:177]
	v_pk_add_f32 v[162:163], v[156:157], v[162:163]
	v_pk_add_f32 v[168:169], v[168:169], v[170:171]
	v_pk_add_f32 v[172:173], v[172:173], v[174:175]
	ds_bpermute_b32 v164, v129, v162
	ds_bpermute_b32 v165, v129, v163
	ds_bpermute_b32 v170, v129, v168
	ds_bpermute_b32 v171, v129, v169
	ds_bpermute_b32 v174, v129, v172
	ds_bpermute_b32 v175, v129, v173
	s_waitcnt lgkmcnt(4)
	v_pk_add_f32 v[162:163], v[162:163], v[164:165]
	ds_bpermute_b32 v160, v186, v158
	s_waitcnt lgkmcnt(3)
	v_pk_add_f32 v[168:169], v[168:169], v[170:171]
	ds_bpermute_b32 v161, v186, v159
	s_waitcnt lgkmcnt(2)
	v_pk_add_f32 v[172:173], v[172:173], v[174:175]
	ds_bpermute_b32 v164, v184, v162
	ds_bpermute_b32 v165, v184, v163
	ds_bpermute_b32 v170, v184, v168
	ds_bpermute_b32 v171, v184, v169
	ds_bpermute_b32 v174, v184, v172
	ds_bpermute_b32 v175, v184, v173
	s_waitcnt lgkmcnt(6)
	v_pk_add_f32 v[158:159], v[158:159], v[160:161]
	s_waitcnt lgkmcnt(4)
	v_pk_add_f32 v[162:163], v[162:163], v[164:165]
	s_waitcnt lgkmcnt(2)
	v_pk_add_f32 v[168:169], v[168:169], v[170:171]
	ds_bpermute_b32 v160, v187, v158
	s_waitcnt lgkmcnt(1)
	v_pk_add_f32 v[172:173], v[172:173], v[174:175]
	ds_bpermute_b32 v161, v187, v159
	ds_bpermute_b32 v164, v185, v162
	ds_bpermute_b32 v165, v185, v163
	ds_bpermute_b32 v170, v185, v168
	ds_bpermute_b32 v171, v185, v169
	ds_bpermute_b32 v174, v185, v172
	ds_bpermute_b32 v175, v185, v173
	ds_bpermute_b32 v176, v187, v166
	ds_bpermute_b32 v177, v187, v167
	s_waitcnt lgkmcnt(8)
	v_pk_add_f32 v[158:159], v[158:159], v[160:161]
	s_waitcnt lgkmcnt(6)
	v_pk_add_f32 v[160:161], v[162:163], v[164:165]
	s_waitcnt lgkmcnt(4)
	v_pk_add_f32 v[168:169], v[168:169], v[170:171]
	s_waitcnt lgkmcnt(2)
	v_pk_add_f32 v[174:175], v[172:173], v[174:175]
	ds_bpermute_b32 v162, v186, v160
	ds_bpermute_b32 v163, v186, v161
	s_waitcnt lgkmcnt(2)
	v_pk_add_f32 v[166:167], v[166:167], v[176:177]
	ds_bpermute_b32 v170, v186, v168
	ds_bpermute_b32 v171, v186, v169
	ds_bpermute_b32 v176, v186, v174
	ds_bpermute_b32 v177, v186, v175
	v_pk_add_f32 v[146:147], v[146:147], v[148:149]
	s_waitcnt lgkmcnt(4)
	v_pk_add_f32 v[160:161], v[160:161], v[162:163]
	s_waitcnt lgkmcnt(2)
	v_pk_add_f32 v[168:169], v[168:169], v[170:171]
	ds_bpermute_b32 v148, v187, v146
	s_waitcnt lgkmcnt(1)
	v_pk_add_f32 v[174:175], v[174:175], v[176:177]
	ds_bpermute_b32 v149, v187, v147
	ds_bpermute_b32 v162, v187, v160
	ds_bpermute_b32 v163, v187, v161
	ds_bpermute_b32 v170, v187, v168
	ds_bpermute_b32 v171, v187, v169
	ds_bpermute_b32 v176, v187, v174
	ds_bpermute_b32 v177, v187, v175
	s_waitcnt lgkmcnt(6)
	v_pk_add_f32 v[146:147], v[146:147], v[148:149]
	s_waitcnt lgkmcnt(4)
	v_pk_add_f32 v[160:161], v[160:161], v[162:163]
	s_waitcnt lgkmcnt(2)
	v_pk_add_f32 v[168:169], v[168:169], v[170:171]
	ds_bpermute_b32 v148, v188, v146
	s_waitcnt lgkmcnt(1)
	v_pk_add_f32 v[174:175], v[174:175], v[176:177]
	ds_bpermute_b32 v149, v188, v147
	ds_bpermute_b32 v154, v188, v152
	ds_bpermute_b32 v155, v188, v153
	ds_bpermute_b32 v156, v188, v150
	ds_bpermute_b32 v157, v188, v151
	ds_bpermute_b32 v164, v188, v158
	ds_bpermute_b32 v165, v188, v159
	ds_bpermute_b32 v162, v188, v160
	ds_bpermute_b32 v163, v188, v161
	ds_bpermute_b32 v172, v188, v166
	ds_bpermute_b32 v173, v188, v167
	ds_bpermute_b32 v170, v188, v168
	ds_bpermute_b32 v171, v188, v169
	ds_bpermute_b32 v176, v188, v174
	ds_bpermute_b32 v177, v188, v175
	s_and_saveexec_b64 s[4:5], s[8:9]
	s_cbranch_execz .LBB0_160
	v_add_u32_e32 v178, v132, v180
	s_waitcnt lgkmcnt(12)
	v_pk_add_f32 v[154:155], v[152:153], v[154:155]
	v_pk_add_f32 v[152:153], v[146:147], v[148:149]
	s_waitcnt lgkmcnt(8)
	v_pk_add_f32 v[148:149], v[158:159], v[164:165]
	v_pk_add_f32 v[146:147], v[150:151], v[156:157]
	ds_write_b128 v178, v[146:149] offset:16
	s_waitcnt lgkmcnt(5)
	v_pk_add_f32 v[148:149], v[166:167], v[172:173]
	v_pk_add_f32 v[146:147], v[160:161], v[162:163]
	ds_write_b128 v178, v[146:149] offset:32
	s_waitcnt lgkmcnt(2)
	v_pk_add_f32 v[148:149], v[174:175], v[176:177]
	v_pk_add_f32 v[146:147], v[168:169], v[170:171]
	ds_write_b128 v178, v[152:155]
	ds_write_b128 v178, v[146:149] offset:48
